# dilated attention: prefetch next item's Q rows + bias entry during the last K/V stage (prologue without global round trips), plus balanced item dealing in phase 10
# speedup vs baseline: 1.0051x; 1.0010x over previous
; #define LAS __attribute__((address_space(3)))
; DI const bf16* dil_hm(Frame& F, int which, int b, int h, int pos) { return (const bf16*)(F.ws + WS_BIG) + (size_t)which * MTOK * 2048 + ((size_t)(b * 16 + h) * SEQ + pos) * 128; }
; template <int D, int STR>
; DI void load_q_frags(Frame& F, bf16x8* qf, const bf16* g0, size_t gstride, LAS unsigned char* buf) {
;     ...
;     for (int hb = 0; hb < NCH; hb += 4) { u32x4 v[4];
; #pragma unroll
;       for (int k = 0; k < 4; ++k) { const int c = tid_ + (hb + k) * NTHR, r = c / CPR, q = c % CPR; v[k] = *(const u32x4*)(g0 + (size_t)r * gstride + q * 8); }
; #pragma unroll
;       for (int k = 0; k < 4; ++k) { const int c = tid_ + (hb + k) * NTHR, r = c / CPR, q = c % CPR; *(LAS u32x4*)(buf + r * STR + q * 16) = v[k]; } }
;     __syncthreads();
; DI void dil_unit(Frame& F, const DilItem& it, bool has_next, const DilItem& nx, RowRegs<128>& RK, RowRegs<128>& RV) {
;     ...
;     LAS unsigned char* Ks = F.lds + ATT_K_OFF; LAS unsigned char* Vs = F.lds + ATT_V_OFF;
;     LAS float* tb = (LAS float*)(F.lds + ATT_TB_OFF);
;     const int lane = F.lane, w = F.wave, tl = lane & 31, hf = lane >> 5;
;     const int d = g == 0 ? 1 : (g == 1 ? 4 : 16);
;     const int m0 = 256 * nb, iq = 32 * w + tl;
;     const size_t tokq = (size_t)b * SEQ + (size_t)(m0 + iq) * d + r;
;     __syncthreads();
;     { const float* bd = (const float*)(F.ws + WS_BIASDIL) + (g * 16 + h) * 160;
;       if (F.tid <= 128) tb[128 - F.tid] = bd[F.tid]; }
;     bf16x8 qf[8];
;     const size_t tok0 = (size_t)b * SEQ + (size_t)m0 * d + r;
;     load_q_frags<128, KSTR128>(F, qf, dil_hm(F, 0, b, h, m0 * d + r), (size_t)d * 128, Ks);
.LBB0_1078:
	s_andn2_b64 vcc, exec, s[0:1]
	s_cbranch_vccnz .LBB0_1120
	s_add_u32 s10, s22, 0x17800000
	s_addc_u32 s11, s23, 0
	v_lshlrev_b32_e32 v148, 2, v146
	v_mov_b32_e32 v149, 0
	s_add_u32 s3, s22, 0xa00000
	v_lshl_add_u64 v[0:1], s[22:23], 0, v[148:149]
	s_mov_b64 s[4:5], 0x180000
	v_lshrrev_b32_e32 v152, 4, v146
	s_addc_u32 s17, s23, 0
	v_lshl_add_u64 v[150:151], v[0:1], 0, s[4:5]
	v_sub_u32_e32 v0, 0x80, v146
	s_add_i32 s4, 0, 0x12000
	s_movk_i32 s45, 0x110
	v_or_b32_e32 v156, 64, v152
	s_lshl_b32 s33, s82, 5
	v_lshl_add_u32 v147, v0, 2, s4
	v_mad_u32_u24 v181, v152, s45, 0
	v_lshlrev_b32_e32 v9, 4, v156
	s_movk_i32 s4, 0x4400
	v_add3_u32 v9, v181, v9, s4
	s_add_u32 s50, s22, 0xf800000
	s_mul_i32 s4, s82, 0x2200
	v_lshrrev_b32_e32 v3, 5, v144
	v_bitop3_b32 v0, v146, 31, v146 bitop3:0xc
	v_add_u32_e32 v6, 0x200, v146
	v_add_u32_e32 v7, 0x600, v146
	s_addc_u32 s51, s23, 0
	s_add_i32 s52, s4, 0
	v_lshlrev_b32_e32 v1, 4, v3
	v_lshlrev_b32_e32 v178, 2, v3
	v_lshrrev_b32_e64 v179, v0, -1
	v_bfe_u32 v3, v146, 2, 2
	v_lshlrev_b32_e32 v0, 1, v146
	v_lshrrev_b32_e32 v154, 4, v6
	v_lshrrev_b32_e32 v158, 4, v7
	s_add_u32 s14, s22, 0x1b800000
	s_waitcnt lgkmcnt(0)
	v_bfe_u32 v10, v146, 5, 1
	v_and_b32_e32 v2, 31, v146
	v_and_b32_e32 v4, 32, v0
	v_and_b32_e32 v0, 15, v146
	v_mad_u32_u24 v183, v154, s45, 0
	v_mad_u32_u24 v184, v158, s45, 0
	v_and_b32_e32 v8, 0x3f0, v146
	v_and_b32_e32 v6, 0x7f0, v6
	v_and_b32_e32 v7, 0xff0, v7
	s_addc_u32 s15, s23, 0
	s_lshl_b32 s6, s82, 8
	v_mul_u32_u24_e32 v10, 0x480, v10
	v_mul_u32_u24_e32 v3, 0x120, v3
	s_movk_i32 s0, 0x81
	v_lshlrev_b32_e32 v5, 3, v146
	v_lshlrev_b32_e32 v182, 4, v0
	v_add_u32_e32 v8, v181, v8
	v_add_u32_e32 v6, v183, v6
	v_add_u32_e32 v7, v184, v7
	v_lshlrev_b32_e32 v0, 3, v0
	s_add_i32 s53, s6, 0
	v_add3_u32 v3, v10, v3, v4
	v_mad_u32_u24 v186, v2, s45, v1
	v_sub_u32_e32 v1, v178, v2
	v_or_b32_e32 v145, s33, v2
	v_cmp_gt_u32_e64 s[0:1], s0, v146
	s_mov_b32 s13, 0
	v_lshlrev_b32_e64 v180, v146, -1
	v_mov_b32_e32 v153, v149
	v_mov_b32_e32 v155, v149
	v_mov_b32_e32 v157, v149
	v_mov_b32_e32 v159, v149
	v_cmp_gt_u32_e64 s[4:5], 32, v144
	s_add_i32 s53, s53, 0x11000
	v_and_or_b32 v185, v5, 24, v3
	v_subrev_u32_e32 v187, s33, v1
	v_add_u32_e32 v188, v8, v182
	v_add_u32_e32 v189, v6, v182
	v_add_u32_e32 v190, v9, v182
	v_add_u32_e32 v191, v7, v182
	v_lshlrev_b32_e32 v148, 1, v0
	s_mov_b32 s16, 0x3e0293ee
	s_mov_b32 s54, 0xf149f2ca
	s_mov_b32 s55, 0x200000
	s_mov_b32 s56, 0x300000
	s_mov_b32 s57, 0x400000
	s_mov_b32 s58, 0x500000
	s_mov_b32 s98, 0
	v_writelane_b32 v229, s98, 58
	s_branch .LBB0_1082
.Lqp10_fast:
	s_cmp_lg_u32 s61, 0
	s_cselect_b64 s[38:39], -1, 0
	s_and_b32 s12, s36, 15
	s_cmp_eq_u32 s61, 1
	s_cselect_b64 s[30:31], -1, 0
	s_and_b64 s[40:41], s[30:31], exec
	s_cselect_b32 s41, 2, 4
	s_cselect_b32 s44, 9, 11
	s_cmp_eq_u32 s37, 1
	s_cselect_b32 s36, 2, 4
	s_cselect_b32 s40, 9, 11
	s_cmp_eq_u32 s37, 0
	s_cselect_b32 s46, 0, s36
	s_cselect_b32 s40, 7, s40
	s_cmp_eq_u32 s61, 0
	s_cselect_b64 s[36:37], -1, 0
	s_and_b64 s[42:43], s[36:37], exec
	s_cselect_b32 s43, 0, s41
	s_cselect_b32 s44, 7, s44
	s_lshr_b32 s48, 16, s43
	s_sub_i32 s41, 4, s43
	s_add_i32 s48, s48, -1
	s_lshr_b32 s41, s12, s41
	s_and_b32 s48, s48, s12
	s_lshr_b32 s12, 16, s46
	s_and_b32 s7, s7, 15
	s_add_i32 s12, s12, -1
	s_ashr_i32 s62, s47, 4
	s_and_b32 s63, s47, 15
	s_sub_i32 s47, 4, s46
	s_and_b32 s49, s12, s7
	s_lshl_b32 s12, s48, 8
	s_lshr_b32 s47, s7, s47
	s_lshl_b32 s7, s12, s43
	s_or_b32 s64, s7, s41
	s_ashr_i32 s7, s6, 31
	s_ashr_i32 s42, s6, 4
	s_lshl_b64 s[6:7], s[6:7], 20
	s_add_u32 s6, s24, s6
	s_addc_u32 s7, s25, s7
	s_lshl_b32 s64, s64, 8
	s_add_u32 s6, s6, s64
	s_addc_u32 s7, s7, 0
	s_cmp_eq_u32 s48, 0
	s_cselect_b64 s[6:7], -1, 0
	v_mov_b32_e32 v161, 0
	v_mov_b32_e32 v160, 0xf149f2ca
	v_mov_b32_e32 v2, v149
	v_mov_b32_e32 v3, v149
	v_mov_b32_e32 v4, v149
	v_mov_b32_e32 v5, v149
	v_mov_b32_e32 v6, v149
	v_mov_b32_e32 v7, v149
	v_mov_b32_e32 v8, v149
	v_mov_b32_e32 v9, v149
	v_mov_b32_e32 v10, v149
	v_mov_b32_e32 v11, v149
	v_mov_b32_e32 v12, v149
	v_mov_b32_e32 v13, v149
	v_mov_b32_e32 v14, v149
	v_mov_b32_e32 v15, v149
	v_add_u32_e32 v0, v181, v182
	ds_write_b128 v0, v[208:211] offset:0
	ds_write_b128 v0, v[212:215] offset:8704
	ds_write_b128 v0, v[216:219] offset:17408
	ds_write_b128 v0, v[220:223] offset:26112
	ds_write_b128 v0, v[224:227] offset:34816
	ds_write_b128 v0, v[232:235] offset:43520
	ds_write_b128 v0, v[236:239] offset:52224
	ds_write_b128 v0, v[240:243] offset:60928
	s_mov_b64 s[98:99], exec
	s_mov_b64 exec, s[0:1]
	ds_write_b32 v147, v228
	s_mov_b64 exec, s[98:99]
	s_branch .Lqp10_join

; DI void dil_unit(Frame& F, const DilItem& it, bool has_next, const DilItem& nx, RowRegs<128>& RK, RowRegs<128>& RV) {
;     ...
;     __syncthreads();
;     { const float* bd = (const float*)(F.ws + WS_BIASDIL) + (g * 16 + h) * 160;
;       if (F.tid <= 128) tb[128 - F.tid] = bd[F.tid]; }
.LBB0_1090:
	s_and_b32 s98, s47, 15
	s_lshl_b32 s99, s37, 4
	s_or_b32 s98, s98, s99
	s_mulk_i32 s98, 0x280
	v_writelane_b32 v229, s98, 56
	s_and_b32 s60, s6, 15
	s_waitcnt vmcnt(0)
	s_barrier
	v_readlane_b32 s98, v229, 58
	s_nop 0
	s_cmp_lg_u32 s98, 0
	s_cbranch_scc1 .Lqp10_fast
	s_and_saveexec_b64 s[30:31], s[0:1]
	s_cbranch_execz .LBB0_1092
	s_lshl_b32 s12, s61, 4
	s_or_b32 s12, s12, s60
	s_mulk_i32 s12, 0xa0
	v_lshl_add_u64 v[0:1], s[12:13], 2, v[150:151]
	global_load_dword v0, v[0:1], off
	s_waitcnt vmcnt(0)
	ds_write_b32 v147, v0

; #define LAS __attribute__((address_space(3)))
; template <int D, int STR>
; DI void load_q_frags(Frame& F, bf16x8* qf, const bf16* g0, size_t gstride, LAS unsigned char* buf) {
;     ...
;     int lane_ = F.lane; asm volatile("" : "+v"(lane_));
;     LAS const unsigned char* qp = buf + (32 * F.wave + (lane_ & 31)) * STR + 16 * (lane_ >> 5);
; #pragma unroll
;     for (int st = 0; st < D / 16; ++st) qf[st] = *(LAS const bf16x8*)(qp + 32 * st);
; DI void dil_unit(Frame& F, const DilItem& it, bool has_next, const DilItem& nx, RowRegs<128>& RK, RowRegs<128>& RV) {
;     ...
;     f32x16 acc[4];
; #pragma unroll
;     for (int e = 0; e < 4; ++e)
; #pragma unroll
;         for (int i = 0; i < 16; ++i) acc[e][i] = 0.f;
;     float m = -1e30f, l = 0.f;
;     const int st_lo = (nb == 0 ? 1 : 0);
.Lqp10_join:
	v_mov_b32_e32 v0, v144
	s_waitcnt lgkmcnt(0)
	s_barrier
	s_nop 0
	v_and_or_b32 v1, v0, 31, s33
	v_ashrrev_i32_e32 v0, 1, v0
	v_mul_lo_u32 v1, v1, s45
	v_and_b32_e32 v0, -16, v0
	v_add3_u32 v0, 0, v1, v0
	ds_read_b128 v[112:115], v0
	ds_read_b128 v[116:119], v0 offset:32
	ds_read_b128 v[120:123], v0 offset:64
	ds_read_b128 v[124:127], v0 offset:96
	ds_read_b128 v[128:131], v0 offset:128
	ds_read_b128 v[132:135], v0 offset:160
	ds_read_b128 v[136:139], v0 offset:192
	ds_read_b128 v[140:143], v0 offset:224
	v_cndmask_b32_e64 v0, 0, 1, s[6:7]
	s_lshl_b32 s6, s49, 8
	s_cmp_eq_u32 s49, 0
	s_cselect_b32 s7, 0, 0xffffff80
	s_add_i32 s7, s7, s6
	s_lshl_b32 s6, s7, s46
	s_or_b32 s64, s6, s47
	s_lshl_b32 s98, s49, 8
	s_lshl_b32 s98, s98, s46
	s_or_b32 s98, s98, s47
	v_writelane_b32 v229, s98, 57
	v_readfirstlane_b32 s6, v0
	v_readfirstlane_b32 s66, v0
	s_lshl_b32 s6, s6, 7
	v_mov_b32_e32 v0, v149
	v_mov_b32_e32 v1, v149
	v_mov_b64_e32 v[30:31], v[14:15]
	v_mov_b64_e32 v[46:47], v[14:15]
	v_mov_b64_e32 v[62:63], v[14:15]
	v_add_lshl_u32 v192, v187, s6, 2
	s_sub_i32 s65, s33, s6
	v_mov_b64_e32 v[28:29], v[12:13]
	v_mov_b64_e32 v[26:27], v[10:11]
	v_mov_b64_e32 v[24:25], v[8:9]
	v_mov_b64_e32 v[22:23], v[6:7]
	v_mov_b64_e32 v[20:21], v[4:5]
	v_mov_b64_e32 v[18:19], v[2:3]
	v_mov_b64_e32 v[16:17], v[0:1]
	v_mov_b64_e32 v[44:45], v[12:13]
	v_mov_b64_e32 v[42:43], v[10:11]
	v_mov_b64_e32 v[40:41], v[8:9]
	v_mov_b64_e32 v[38:39], v[6:7]
	v_mov_b64_e32 v[36:37], v[4:5]
	v_mov_b64_e32 v[34:35], v[2:3]
	v_mov_b64_e32 v[32:33], v[0:1]
	v_mov_b64_e32 v[60:61], v[12:13]
	v_mov_b64_e32 v[58:59], v[10:11]
	v_mov_b64_e32 v[56:57], v[8:9]
	v_mov_b64_e32 v[54:55], v[6:7]
	v_mov_b64_e32 v[52:53], v[4:5]
	v_mov_b64_e32 v[50:51], v[2:3]
	v_mov_b64_e32 v[48:49], v[0:1]

; template <int D, int STR>
; DI void load_q_frags(Frame& F, bf16x8* qf, const bf16* g0, size_t gstride, LAS unsigned char* buf) {
;     ...
;     for (int hb = 0; hb < NCH; hb += 4) { u32x4 v[4];
; #pragma unroll
;       for (int k = 0; k < 4; ++k) { const int c = tid_ + (hb + k) * NTHR, r = c / CPR, q = c % CPR; v[k] = *(const u32x4*)(g0 + (size_t)r * gstride + q * 8); }
; DI void dil_unit(Frame& F, const DilItem& it, bool has_next, const DilItem& nx, RowRegs<128>& RK, RowRegs<128>& RV) {
;     ...
;         if (st < 2) { size_t gs; const bf16* kg = dil_kptr(F, it, st + 1, gs);
;             fetch_rows128<128>(RK, kg, gs, F.tid); fetch_rows128<128>(RV, kg + (size_t)MTOK * 2048, gs, F.tid); }
;         else if (has_next) { size_t gs; const bf16* kg = dil_kptr(F, nx, nx.nb == 0 ? 1 : 0, gs);
;             fetch_rows128<128>(RK, kg, gs, F.tid); fetch_rows128<128>(RV, kg + (size_t)MTOK * 2048, gs, F.tid); }
.LBB0_1100:
	s_cmp_lg_u32 s66, 2
	s_cbranch_scc1 .Lqp10_skip
	s_cmp_eq_u64 s[34:35], 0
	s_cbranch_scc1 .Lqp10_skip
	v_readlane_b32 s100, v229, 56
	s_mov_b32 s101, 0
	v_readlane_b32 s98, v229, 57
	s_nop 0
	v_lshl_add_u64 v[64:65], v[150:151], 0, s[100:101]
	global_load_dword v228, v[64:65], off
	s_lshl_b32 s100, 0x100, s40
	s_sub_i32 s98, s98, s64
	s_lshl_b32 s98, s98, 8
	s_add_u32 s98, s46, s98
	s_addc_u32 s99, s47, 0
	s_sub_u32 s98, s98, 0x4000000
	s_subb_u32 s99, s99, 0
	v_lshlrev_b64 v[64:65], s40, v[152:153]
	v_lshl_add_u64 v[64:65], v[64:65], 1, s[98:99]
	v_lshl_add_u64 v[64:65], v[64:65], 0, v[148:149]
	v_lshl_add_u64 v[66:67], v[64:65], 0, s[100:101]
	global_load_dwordx4 v[208:211], v[64:65], off
	global_load_dwordx4 v[224:227], v[66:67], off
	v_lshlrev_b64 v[64:65], s40, v[154:155]
	v_lshl_add_u64 v[64:65], v[64:65], 1, s[98:99]
	v_lshl_add_u64 v[64:65], v[64:65], 0, v[148:149]
	v_lshl_add_u64 v[66:67], v[64:65], 0, s[100:101]
	global_load_dwordx4 v[212:215], v[64:65], off
	global_load_dwordx4 v[232:235], v[66:67], off
	v_lshlrev_b64 v[64:65], s40, v[156:157]
	v_lshl_add_u64 v[64:65], v[64:65], 1, s[98:99]
	v_lshl_add_u64 v[64:65], v[64:65], 0, v[148:149]
	v_lshl_add_u64 v[66:67], v[64:65], 0, s[100:101]
	global_load_dwordx4 v[216:219], v[64:65], off
	global_load_dwordx4 v[236:239], v[66:67], off
	v_lshlrev_b64 v[64:65], s40, v[158:159]
	v_lshl_add_u64 v[64:65], v[64:65], 1, s[98:99]
	v_lshl_add_u64 v[64:65], v[64:65], 0, v[148:149]
	v_lshl_add_u64 v[66:67], v[64:65], 0, s[100:101]
	global_load_dwordx4 v[220:223], v[64:65], off
	global_load_dwordx4 v[240:243], v[66:67], off
	s_mov_b32 s98, 1
	v_writelane_b32 v229, s98, 58

; #define LAS __attribute__((address_space(3)))
; DI const bf16* dil_hm(Frame& F, int which, int b, int h, int pos) { return (const bf16*)(F.ws + WS_BIG) + (size_t)which * MTOK * 2048 + ((size_t)(b * 16 + h) * SEQ + pos) * 128; }
; DI void dil_unit(Frame& F, const DilItem& it, bool has_next, const DilItem& nx, RowRegs<128>& RK, RowRegs<128>& RV) {
;     ...
;     LAS unsigned char* Ks = F.lds + ATT_K_OFF; LAS unsigned char* Vs = F.lds + ATT_V_OFF;
;     LAS float* tb = (LAS float*)(F.lds + ATT_TB_OFF);
;     const int lane = F.lane, w = F.wave, tl = lane & 31, hf = lane >> 5;
;     const int d = g == 0 ? 1 : (g == 1 ? 4 : 16);
;     const int m0 = 256 * nb, iq = 32 * w + tl;
;     const size_t tokq = (size_t)b * SEQ + (size_t)(m0 + iq) * d + r;
;     __syncthreads();
;     { const float* bd = (const float*)(F.ws + WS_BIASDIL) + (g * 16 + h) * 160;
;       if (F.tid <= 128) tb[128 - F.tid] = bd[F.tid]; }
;     bf16x8 qf[8];
;     const size_t tok0 = (size_t)b * SEQ + (size_t)m0 * d + r;
;     load_q_frags<128, KSTR128>(F, qf, dil_hm(F, 0, b, h, m0 * d + r), (size_t)d * 128, Ks);
.LBB0_1170:
	s_cmp_lt_i32 s80, 12
	s_cselect_b64 s[4:5], -1, 0
	s_and_b64 s[6:7], s[4:5], s[0:1]
	s_cmpk_lt_i32 s19, 0x400
	s_cselect_b64 s[0:1], -1, 0
	s_and_b64 s[0:1], s[6:7], s[0:1]
	s_andn2_b64 vcc, exec, s[0:1]
	s_cbranch_vccnz .LBB0_1201
	s_and_b32 s0, s19, 15
	s_bfe_u32 s1, s19, 0x40004
	s_lshl_b32 s3, s0, 8
	s_cmp_eq_u32 s0, 0
	s_cselect_b32 s0, 0, 0xffffff80
	s_add_i32 s0, s0, s3
	s_add_u32 s3, s22, 0xf800000
	s_addc_u32 s15, s23, 0
	s_ashr_i32 s4, s19, 4
	s_and_b32 s4, s4, -16
	s_or_b32 s4, s4, s1
	s_ashr_i32 s5, s4, 31
	s_ashr_i32 s1, s0, 31
	s_lshl_b64 s[4:5], s[4:5], 20
	s_add_u32 s4, s3, s4
	s_addc_u32 s5, s15, s5
	s_lshl_b64 s[0:1], s[0:1], 8
	s_waitcnt lgkmcnt(0)
	v_lshlrev_b32_e32 v12, 3, v146
	s_add_u32 s0, s4, s0
	v_lshlrev_b32_e32 v2, 4, v146
	v_add_u32_e32 v4, 0x1000, v12
	s_addc_u32 s1, s5, s1
	v_and_b32_e32 v148, 0x3f00, v2
	v_mov_b32_e32 v149, 0
	v_and_b32_e32 v4, 0x3f80, v4
	v_lshl_add_u64 v[0:1], s[0:1], 0, v[148:149]
	v_and_b32_e32 v2, 0xf0, v2
	v_mov_b32_e32 v3, v149
	v_lshlrev_b32_e32 v4, 1, v4
	v_mov_b32_e32 v5, v149
	v_add_u32_e32 v8, 0x3000, v12
	v_lshl_add_u64 v[0:1], v[0:1], 0, v[2:3]
	v_lshl_add_u64 v[6:7], s[0:1], 0, v[4:5]
	v_and_b32_e32 v8, 0x7f80, v8
	v_lshl_add_u64 v[6:7], v[6:7], 0, v[2:3]
	global_load_dwordx4 v[80:83], v[0:1], off
	global_load_dwordx4 v[84:87], v[6:7], off
	v_or_b32_e32 v0, 0x4000, v148
	v_mov_b32_e32 v1, v149
	v_lshlrev_b32_e32 v8, 1, v8
	v_mov_b32_e32 v9, v149
	v_lshl_add_u64 v[6:7], s[0:1], 0, v[0:1]
	v_lshl_add_u64 v[10:11], s[0:1], 0, v[8:9]
	s_add_u32 s0, s0, 0x4000000
	v_lshl_add_u64 v[6:7], v[6:7], 0, v[2:3]
	s_addc_u32 s1, s1, 0
	v_lshl_add_u64 v[10:11], v[10:11], 0, v[2:3]
	global_load_dwordx4 v[88:91], v[6:7], off
	global_load_dwordx4 v[92:95], v[10:11], off
	v_lshl_add_u64 v[6:7], s[0:1], 0, v[148:149]
	v_lshl_add_u64 v[4:5], s[0:1], 0, v[4:5]
	v_lshl_add_u64 v[6:7], v[6:7], 0, v[2:3]
	v_lshl_add_u64 v[4:5], v[4:5], 0, v[2:3]
	v_lshl_add_u64 v[0:1], s[0:1], 0, v[0:1]
	global_load_dwordx4 v[96:99], v[6:7], off
	global_load_dwordx4 v[100:103], v[4:5], off
	v_lshl_add_u64 v[0:1], v[0:1], 0, v[2:3]
	v_lshl_add_u64 v[4:5], s[0:1], 0, v[8:9]
	v_lshl_add_u64 v[2:3], v[4:5], 0, v[2:3]
	global_load_dwordx4 v[104:107], v[0:1], off
	global_load_dwordx4 v[108:111], v[2:3], off
	v_lshlrev_b32_e32 v148, 2, v146
	v_lshl_add_u64 v[0:1], s[22:23], 0, v[148:149]
	s_mov_b64 s[4:5], 0x180000
	s_lshl_b32 s33, s82, 5
	v_lshl_add_u64 v[150:151], v[0:1], 0, s[4:5]
	s_add_i32 s4, 0, 0x12000
	s_add_u32 s10, s22, 0x17800000
	v_lshrrev_b32_e32 v152, 4, v146
	s_addc_u32 s11, s23, 0
	v_sub_u32_e32 v0, 0x80, v146
	s_movk_i32 s44, 0x110
	v_or_b32_e32 v156, 64, v152
	s_add_u32 s12, s22, 0x1b800000
	v_lshrrev_b32_e32 v3, 5, v144
	v_lshl_add_u32 v145, v0, 2, s4
	v_bitop3_b32 v0, v146, 31, v146 bitop3:0xc
	v_mad_u32_u24 v180, v152, s44, 0
	v_add_u32_e32 v5, 0x200, v146
	v_add_u32_e32 v6, 0x600, v146
	v_lshlrev_b32_e32 v8, 4, v156
	s_movk_i32 s4, 0x4400
	s_addc_u32 s13, s23, 0
	v_lshlrev_b32_e32 v1, 4, v3
	v_lshlrev_b32_e32 v147, 2, v3
	v_lshrrev_b32_e64 v178, v0, -1
	v_bfe_u32 v3, v146, 2, 2
	v_lshlrev_b32_e32 v0, 1, v146
	v_lshrrev_b32_e32 v154, 4, v5
	v_lshrrev_b32_e32 v158, 4, v6
	v_add3_u32 v8, v180, v8, s4
	s_add_u32 s45, s22, 0xa00000
	s_mul_i32 s4, s82, 0x2200
	v_bfe_u32 v9, v146, 5, 1
	v_and_b32_e32 v2, 31, v146
	v_and_b32_e32 v4, 32, v0
	v_and_b32_e32 v0, 15, v146
	v_mad_u32_u24 v182, v154, s44, 0
	v_mad_u32_u24 v183, v158, s44, 0
	v_and_b32_e32 v7, 0x3f0, v146
	v_and_b32_e32 v5, 0x7f0, v5
	v_and_b32_e32 v6, 0xff0, v6
	s_addc_u32 s46, s23, 0
	s_add_i32 s47, s4, 0
	s_lshl_b32 s4, s82, 8
	v_mul_u32_u24_e32 v9, 0x480, v9
	v_mul_u32_u24_e32 v3, 0x120, v3
	s_movk_i32 s0, 0x81
	v_lshlrev_b32_e32 v181, 4, v0
	v_add_u32_e32 v7, v180, v7
	v_add_u32_e32 v5, v182, v5
	v_add_u32_e32 v6, v183, v6
	v_lshlrev_b32_e32 v0, 3, v0
	s_add_i32 s48, s4, 0
	v_add3_u32 v3, v9, v3, v4
	v_mad_u32_u24 v185, v2, s44, v1
	v_sub_u32_e32 v1, v147, v2
	s_mov_b32 s9, 0
	v_cmp_gt_u32_e64 s[0:1], s0, v146
	v_lshlrev_b32_e64 v179, v146, -1
	v_mov_b32_e32 v153, v149
	v_mov_b32_e32 v155, v149
	v_mov_b32_e32 v157, v149
	v_mov_b32_e32 v159, v149
	s_add_i32 s48, s48, 0x11000
	v_and_or_b32 v184, v12, 24, v3
	v_subrev_u32_e32 v186, s33, v1
	v_add_u32_e32 v187, v7, v181
	v_add_u32_e32 v188, v5, v181
	v_add_u32_e32 v189, v8, v181
	v_add_u32_e32 v190, v6, v181
	v_lshlrev_b32_e32 v148, 1, v0
	s_mov_b32 s14, 0x3e0293ee
	s_mov_b32 s49, 0xf149f2ca
	s_mov_b32 s50, 0x200000
	s_mov_b32 s51, 0x300000
	s_mov_b32 s52, 0x400000
	s_mov_b32 s53, 0x500000
	s_mov_b32 s98, 0
	v_writelane_b32 v229, s98, 58
	s_branch .LBB0_1173
.Lqp11_fast:
	s_and_b32 s29, s19, 15
	s_ashr_i32 s28, s19, 8
	s_and_b32 s19, s5, 15
	s_cmp_eq_u32 s34, 1
	s_cselect_b32 s5, 2, 4
	s_cselect_b32 s8, 9, 11
	s_cmp_eq_u32 s34, 0
	s_cselect_b32 s5, 0, s5
	s_cselect_b32 s8, 7, s8
	s_lshr_b32 s34, 16, s5
	s_add_i32 s34, s34, -1
	s_and_b32 s39, s34, s19
	s_lshl_b32 s34, s28, 4
	s_sub_i32 s35, 4, s5
	s_or_b32 s34, s34, s55
	s_lshr_b32 s38, s19, s35
	s_ashr_i32 s35, s34, 31
	s_lshl_b32 s19, s29, 8
	s_lshl_b64 s[34:35], s[34:35], 20
	s_add_u32 s36, s24, s34
	s_addc_u32 s37, s25, s35
	s_lshl_b32 s40, s29, 16
	s_add_u32 s36, s36, s40
	s_addc_u32 s37, s37, 0
	s_cmp_eq_u32 s29, 0
	s_cselect_b64 s[36:37], -1, 0
	s_lshl_b32 s29, s39, 8
	s_cmp_eq_u32 s39, 0
	v_mov_b32_e32 v161, 0
	v_mov_b32_e32 v160, 0xf149f2ca
	v_mov_b32_e32 v2, v149
	v_mov_b32_e32 v3, v149
	v_mov_b32_e32 v4, v149
	v_mov_b32_e32 v5, v149
	v_mov_b32_e32 v6, v149
	v_mov_b32_e32 v7, v149
	v_mov_b32_e32 v8, v149
	v_mov_b32_e32 v9, v149
	v_mov_b32_e32 v10, v149
	v_mov_b32_e32 v11, v149
	v_mov_b32_e32 v12, v149
	v_mov_b32_e32 v13, v149
	v_mov_b32_e32 v14, v149
	v_mov_b32_e32 v15, v149
	v_add_u32_e32 v0, v180, v181
	ds_write_b128 v0, v[208:211] offset:0
	ds_write_b128 v0, v[212:215] offset:8704
	ds_write_b128 v0, v[216:219] offset:17408
	ds_write_b128 v0, v[220:223] offset:26112
	ds_write_b128 v0, v[224:227] offset:34816
	ds_write_b128 v0, v[232:235] offset:43520
	ds_write_b128 v0, v[236:239] offset:52224
	ds_write_b128 v0, v[240:243] offset:60928
	s_mov_b64 s[98:99], exec
	s_mov_b64 exec, s[0:1]
	ds_write_b32 v145, v228
	s_mov_b64 exec, s[98:99]
	s_branch .Lqp11_join

; DI void dil_unit(Frame& F, const DilItem& it, bool has_next, const DilItem& nx, RowRegs<128>& RK, RowRegs<128>& RV) {
;     ...
;     __syncthreads();
;     { const float* bd = (const float*)(F.ws + WS_BIASDIL) + (g * 16 + h) * 160;
;       if (F.tid <= 128) tb[128 - F.tid] = bd[F.tid]; }
.LBB0_1177:
	s_bfe_u32 s98, s5, 0x40004
	s_mulk_i32 s98, 0x280
	v_writelane_b32 v229, s98, 56
	s_bfe_u32 s55, s19, 0x40004
	s_waitcnt vmcnt(0)
	s_barrier
	v_readlane_b32 s98, v229, 58
	s_nop 0
	s_cmp_lg_u32 s98, 0
	s_cbranch_scc1 .Lqp11_fast
	s_and_saveexec_b64 s[28:29], s[0:1]
	s_cbranch_execz .LBB0_1179
	s_mul_i32 s8, s55, 0x280
	v_lshl_add_u64 v[0:1], v[150:151], 0, s[8:9]
	global_load_dword v0, v[0:1], off
	s_waitcnt vmcnt(0)
	ds_write_b32 v145, v0

; #define LAS __attribute__((address_space(3)))
; template <int D, int STR>
; DI void load_q_frags(Frame& F, bf16x8* qf, const bf16* g0, size_t gstride, LAS unsigned char* buf) {
;     ...
;     int lane_ = F.lane; asm volatile("" : "+v"(lane_));
;     LAS const unsigned char* qp = buf + (32 * F.wave + (lane_ & 31)) * STR + 16 * (lane_ >> 5);
; #pragma unroll
;     for (int st = 0; st < D / 16; ++st) qf[st] = *(LAS const bf16x8*)(qp + 32 * st);
; DI void dil_unit(Frame& F, const DilItem& it, bool has_next, const DilItem& nx, RowRegs<128>& RK, RowRegs<128>& RV) {
;     ...
;     f32x16 acc[4];
; #pragma unroll
;     for (int e = 0; e < 4; ++e)
; #pragma unroll
;         for (int i = 0; i < 16; ++i) acc[e][i] = 0.f;
;     float m = -1e30f, l = 0.f;
;     const int st_lo = (nb == 0 ? 1 : 0);
.Lqp11_join:
	v_mov_b32_e32 v0, v144
	s_waitcnt lgkmcnt(0)
	s_barrier
	s_nop 0
	v_and_or_b32 v1, v0, 31, s33
	v_ashrrev_i32_e32 v0, 1, v0
	v_mul_lo_u32 v1, v1, s44
	v_and_b32_e32 v0, -16, v0
	v_add3_u32 v0, 0, v1, v0
	ds_read_b128 v[112:115], v0
	ds_read_b128 v[116:119], v0 offset:32
	ds_read_b128 v[120:123], v0 offset:64
	ds_read_b128 v[124:127], v0 offset:96
	ds_read_b128 v[128:131], v0 offset:128
	ds_read_b128 v[132:135], v0 offset:160
	ds_read_b128 v[136:139], v0 offset:192
	ds_read_b128 v[140:143], v0 offset:224
	v_cndmask_b32_e64 v0, 0, 1, s[36:37]
	s_cselect_b32 s36, 0, 0xffffff80
	s_add_i32 s36, s36, s29
	s_lshl_b32 s98, s29, s5
	s_or_b32 s98, s98, s38
	v_writelane_b32 v229, s98, 57
	s_lshl_b32 s5, s36, s5
	s_or_b32 s29, s5, s38
	s_ashr_i32 s5, s4, 31
	s_lshl_b64 s[36:37], s[4:5], 20
	v_readfirstlane_b32 s4, v0
	v_readfirstlane_b32 s57, v0
	s_lshl_b32 s4, s4, 7
	v_mov_b32_e32 v0, v149
	v_mov_b32_e32 v1, v149
	v_mov_b64_e32 v[30:31], v[14:15]
	v_mov_b64_e32 v[46:47], v[14:15]
	v_mov_b64_e32 v[62:63], v[14:15]
	v_add_lshl_u32 v191, v186, s4, 2
	s_sub_i32 s56, s33, s4
	v_mov_b64_e32 v[28:29], v[12:13]
	v_mov_b64_e32 v[26:27], v[10:11]
	v_mov_b64_e32 v[24:25], v[8:9]
	v_mov_b64_e32 v[22:23], v[6:7]
	v_mov_b64_e32 v[20:21], v[4:5]
	v_mov_b64_e32 v[18:19], v[2:3]
	v_mov_b64_e32 v[16:17], v[0:1]
	v_mov_b64_e32 v[44:45], v[12:13]
	v_mov_b64_e32 v[42:43], v[10:11]
	v_mov_b64_e32 v[40:41], v[8:9]
	v_mov_b64_e32 v[38:39], v[6:7]
	v_mov_b64_e32 v[36:37], v[4:5]
	v_mov_b64_e32 v[34:35], v[2:3]
	v_mov_b64_e32 v[32:33], v[0:1]
	v_mov_b64_e32 v[60:61], v[12:13]
	v_mov_b64_e32 v[58:59], v[10:11]
	v_mov_b64_e32 v[56:57], v[8:9]
	v_mov_b64_e32 v[54:55], v[6:7]
	v_mov_b64_e32 v[52:53], v[4:5]
	v_mov_b64_e32 v[50:51], v[2:3]
	v_mov_b64_e32 v[48:49], v[0:1]

; template <int D, int STR>
; DI void load_q_frags(Frame& F, bf16x8* qf, const bf16* g0, size_t gstride, LAS unsigned char* buf) {
;     ...
;     for (int hb = 0; hb < NCH; hb += 4) { u32x4 v[4];
; #pragma unroll
;       for (int k = 0; k < 4; ++k) { const int c = tid_ + (hb + k) * NTHR, r = c / CPR, q = c % CPR; v[k] = *(const u32x4*)(g0 + (size_t)r * gstride + q * 8); }
; DI void dil_unit(Frame& F, const DilItem& it, bool has_next, const DilItem& nx, RowRegs<128>& RK, RowRegs<128>& RV) {
;     ...
;         if (st < 2) { size_t gs; const bf16* kg = dil_kptr(F, it, st + 1, gs);
;             fetch_rows128<128>(RK, kg, gs, F.tid); fetch_rows128<128>(RV, kg + (size_t)MTOK * 2048, gs, F.tid); }
;         else if (has_next) { size_t gs; const bf16* kg = dil_kptr(F, nx, nx.nb == 0 ? 1 : 0, gs);
;             fetch_rows128<128>(RK, kg, gs, F.tid); fetch_rows128<128>(RV, kg + (size_t)MTOK * 2048, gs, F.tid); }
.LBB0_1186:
	s_cmp_lg_u32 s57, 2
	s_cbranch_scc1 .Lqp11_skip
	s_cmp_eq_u64 s[30:31], 0
	s_cbranch_scc1 .Lqp11_skip
	v_readlane_b32 s100, v229, 56
	s_mov_b32 s101, 0
	v_readlane_b32 s98, v229, 57
	s_nop 0
	v_lshl_add_u64 v[64:65], v[150:151], 0, s[100:101]
	global_load_dword v228, v[64:65], off
	s_lshl_b32 s100, 0x100, s8
	s_sub_i32 s98, s98, s29
	s_lshl_b32 s98, s98, 8
	s_add_u32 s98, s38, s98
	s_addc_u32 s99, s39, 0
	s_sub_u32 s98, s98, 0x4000000
	s_subb_u32 s99, s99, 0
	v_lshlrev_b64 v[64:65], s8, v[152:153]
	v_lshl_add_u64 v[64:65], v[64:65], 1, s[98:99]
	v_lshl_add_u64 v[64:65], v[64:65], 0, v[148:149]
	v_lshl_add_u64 v[66:67], v[64:65], 0, s[100:101]
	global_load_dwordx4 v[208:211], v[64:65], off
	global_load_dwordx4 v[224:227], v[66:67], off
	v_lshlrev_b64 v[64:65], s8, v[154:155]
	v_lshl_add_u64 v[64:65], v[64:65], 1, s[98:99]
	v_lshl_add_u64 v[64:65], v[64:65], 0, v[148:149]
	v_lshl_add_u64 v[66:67], v[64:65], 0, s[100:101]
	global_load_dwordx4 v[212:215], v[64:65], off
	global_load_dwordx4 v[232:235], v[66:67], off
	v_lshlrev_b64 v[64:65], s8, v[156:157]
	v_lshl_add_u64 v[64:65], v[64:65], 1, s[98:99]
	v_lshl_add_u64 v[64:65], v[64:65], 0, v[148:149]
	v_lshl_add_u64 v[66:67], v[64:65], 0, s[100:101]
	global_load_dwordx4 v[216:219], v[64:65], off
	global_load_dwordx4 v[236:239], v[66:67], off
	v_lshlrev_b64 v[64:65], s8, v[158:159]
	v_lshl_add_u64 v[64:65], v[64:65], 1, s[98:99]
	v_lshl_add_u64 v[64:65], v[64:65], 0, v[148:149]
	v_lshl_add_u64 v[66:67], v[64:65], 0, s[100:101]
	global_load_dwordx4 v[220:223], v[64:65], off
	global_load_dwordx4 v[240:243], v[66:67], off
	s_mov_b32 s98, 1
	v_writelane_b32 v229, s98, 58
